# code placement: mixer-A tile-loop head pinned to a 32-byte boundary (.p2align 5), plus unit-boundary edits (batched O readback, no store drain before next unit, zeroing before DMA wait)
# baseline (speedup 1.0000x reference)
.Lattn_prio_skip_a:
	s_barrier
	s_branch .LBB0_408
	.p2align 5
